# speedup vs baseline: 1.0019x; 1.0019x over previous
; __device__ __forceinline__ float bfs(short h) { return __uint_as_float(((unsigned)(u16)h) << 16); }
; __device__ __forceinline__ void phase_ret_o(PP p, const int g_wid, int layer) {
;     ...
;     bf16x8 qa[4];
;     {
;       int qpos = t0 + wid * 16 + fr;
;       if (qpos < L) {
;         const u16* qp = Pr + (long)(base + qpos) * 2048 + hd * 128 + fq * 8;
;         bf16x8 x0 = *reinterpret_cast<const bf16x8*>(qp), x1v = *reinterpret_cast<const bf16x8*>(qp + 32);
;         bf16x8 x2v = *reinterpret_cast<const bf16x8*>(qp + 64), x3 = *reinterpret_cast<const bf16x8*>(qp + 96);
;         const float2* cs = p->sincos + qpos * 64 + fq * 8;
;         float q0[8], q1[8], q2[8], q3[8];
; #pragma unroll
;         for (int i = 0; i < 8; ++i) {
;           float2 ca = cs[i], cb = cs[32 + i];
;           float a1 = bfs(x0[i]), a2 = bfs(x2v[i]);
;           q0[i] = a1 * ca.x - a2 * ca.y;
;           q2[i] = a2 * ca.x + a1 * ca.y;
;           float b1 = bfs(x1v[i]), b2 = bfs(x3[i]);
;           q1[i] = b1 * cb.x - b2 * cb.y;
;           q3[i] = b2 * cb.x + b1 * cb.y;
;         }
;         qa[0] = pack8(q0); qa[1] = pack8(q1); qa[2] = pack8(q2); qa[3] = pack8(q3);
.LBB0_197:
	s_or_b64 exec, exec, s[6:7]
	v_lshrrev_b32_e32 v203, 2, v155
	v_and_b32_e32 v204, 3, v155
	v_lshlrev_b32_e32 v204, 3, v204
	v_add_u32_e32 v168, s13, v124
	v_or_b32_e32 v66, v168, v203
	v_mov_b32_e32 v62, 0
	v_cmp_gt_i32_e32 vcc, s35, v66
	v_mov_b32_e32 v63, v62
	v_mov_b32_e32 v64, v62
	v_mov_b32_e32 v65, v62
	v_mov_b32_e32 v58, v62
	v_mov_b32_e32 v59, v62
	v_mov_b32_e32 v60, v62
	v_mov_b32_e32 v61, v62
	v_mov_b32_e32 v54, v62
	v_mov_b32_e32 v55, v62
	v_mov_b32_e32 v56, v62
	v_mov_b32_e32 v57, v62
	v_mov_b32_e32 v50, v62
	v_mov_b32_e32 v51, v62
	v_mov_b32_e32 v52, v62
	v_mov_b32_e32 v53, v62
	s_and_saveexec_b64 s[6:7], vcc
	s_cbranch_execz .LBB0_199
	v_add_u32_e32 v50, s34, v66
	v_ashrrev_i32_e32 v51, 31, v50
	v_lshlrev_b64 v[50:51], 12, v[50:51]
	v_lshl_add_u64 v[50:51], s[14:15], 0, v[50:51]
	s_lshl_b32 s54, s31, 8
	v_lshl_add_u64 v[50:51], v[50:51], 0, s[54:55]
	v_lshlrev_b32_e32 v0, 1, v204
	v_readlane_b32 s8, v254, 0
	v_lshl_add_u64 v[54:55], v[50:51], 0, v[0:1]
	v_readlane_b32 s9, v254, 1
	global_load_dwordx4 v[58:61], v[54:55], off
	global_load_dwordx4 v[50:53], v[54:55], off offset:64
	global_load_dwordx4 v[62:65], v[54:55], off offset:128
	s_nop 0
	global_load_dwordx4 v[54:57], v[54:55], off offset:192
	s_load_dwordx2 s[8:9], s[8:9], 0xd8
	v_lshlrev_b32_e32 v66, 6, v66
	v_ashrrev_i32_e32 v67, 31, v66
	v_lshlrev_b32_e32 v0, 3, v204
	s_waitcnt lgkmcnt(0)
	v_lshl_add_u64 v[66:67], v[66:67], 3, s[8:9]
	v_lshl_add_u64 v[108:109], v[66:67], 0, v[0:1]
	global_load_dwordx4 v[66:69], v[108:109], off offset:48
	global_load_dwordx4 v[74:77], v[108:109], off offset:32
	global_load_dwordx4 v[86:89], v[108:109], off offset:16
	global_load_dwordx4 v[118:121], v[108:109], off
	global_load_dwordx4 v[70:73], v[108:109], off offset:304
	global_load_dwordx4 v[78:81], v[108:109], off offset:288
	global_load_dwordx4 v[82:85], v[108:109], off offset:272
	global_load_dwordx4 v[190:193], v[108:109], off offset:256
	s_waitcnt vmcnt(11)
	v_and_b32_e32 v197, 0xffff0000, v58
	v_lshlrev_b32_e32 v114, 16, v58
	s_waitcnt vmcnt(9)
	v_lshlrev_b32_e32 v196, 16, v62
	v_and_b32_e32 v115, 0xffff0000, v62
	v_mov_b32_e32 v201, v197
	v_mov_b32_e32 v200, v114
	v_lshlrev_b32_e32 v58, 16, v63
	s_waitcnt vmcnt(7)
	v_mov_b32_e32 v90, v67
	s_waitcnt vmcnt(6)
	v_mov_b32_e32 v92, v75
	s_waitcnt vmcnt(5)
	v_mov_b32_e32 v62, v86
	s_waitcnt vmcnt(4)
	v_mov_b32_e32 v198, v118
	v_mov_b32_e32 v199, v121
	v_mov_b32_e32 v112, v119
	v_mov_b32_e32 v113, v120
	v_pk_mul_f32 v[198:199], v[198:199], v[196:197]
	v_mov_b32_e32 v197, v115
	v_pk_fma_f32 v[112:113], v[112:113], v[114:115], v[198:199]
	v_mov_b32_e32 v199, v120
	v_mov_b32_e32 v120, v119
	v_mov_b32_e32 v198, v118
	v_pk_mul_f32 v[114:115], v[120:121], v[196:197]
	v_and_b32_e32 v197, 0xffff0000, v50
	v_lshlrev_b32_e32 v196, 16, v54
	s_waitcnt vmcnt(0)
	v_mov_b32_e32 v118, v190
	v_mov_b32_e32 v119, v193
	v_mov_b32_e32 v194, v191
	v_mov_b32_e32 v195, v192
	v_and_b32_e32 v121, 0xffff0000, v54
	v_lshlrev_b32_e32 v120, 16, v50
	v_pk_mul_f32 v[118:119], v[118:119], v[196:197]
	v_mov_b32_e32 v192, v191
	v_pk_fma_f32 v[118:119], v[194:195], v[120:121], v[118:119]
	v_mov_b32_e32 v194, v190
	v_and_b32_e32 v191, 0xffff0000, v63
	v_lshlrev_b32_e32 v190, 16, v59
	v_and_b32_e32 v59, 0xffff0000, v59
	v_mov_b32_e32 v63, v89
	v_mov_b32_e32 v122, v87
	v_mov_b32_e32 v123, v88
	v_pk_fma_f32 v[114:115], v[198:199], v[200:201], v[114:115] neg_lo:[0,0,1] neg_hi:[0,0,1]
	v_mov_b32_e32 v199, v197
	v_mov_b32_e32 v197, v121
	v_pk_mul_f32 v[62:63], v[62:63], v[58:59]
	v_mov_b32_e32 v198, v120
	v_pk_mul_f32 v[120:121], v[192:193], v[196:197]
	v_pk_fma_f32 v[122:123], v[122:123], v[190:191], v[62:63]
	v_mov_b32_e32 v63, v88
	v_mov_b32_e32 v193, v59
	v_mov_b32_e32 v88, v87
	v_mov_b32_e32 v59, v191
	v_mov_b32_e32 v62, v86
	v_mov_b32_e32 v192, v190
	v_pk_mul_f32 v[58:59], v[88:89], v[58:59]
	v_lshlrev_b32_e32 v50, 16, v55
	v_pk_fma_f32 v[58:59], v[62:63], v[192:193], v[58:59] neg_lo:[0,0,1] neg_hi:[0,0,1]
	v_and_b32_e32 v63, 0xffff0000, v55
	v_lshlrev_b32_e32 v62, 16, v51
	v_and_b32_e32 v51, 0xffff0000, v51
	v_mov_b32_e32 v54, v82
	v_mov_b32_e32 v55, v85
	v_mov_b32_e32 v116, v83
	v_mov_b32_e32 v117, v84
	v_pk_mul_f32 v[54:55], v[54:55], v[50:51]
	v_mov_b32_e32 v89, v51
	v_pk_fma_f32 v[86:87], v[116:117], v[62:63], v[54:55]
	v_mov_b32_e32 v55, v84
	v_mov_b32_e32 v84, v83
	v_mov_b32_e32 v51, v63
	v_mov_b32_e32 v54, v82
	v_mov_b32_e32 v88, v62
	v_pk_mul_f32 v[50:51], v[84:85], v[50:51]
	v_and_b32_e32 v63, 0xffff0000, v60
	v_pk_fma_f32 v[50:51], v[54:55], v[88:89], v[50:51] neg_lo:[0,0,1] neg_hi:[0,0,1]
	v_and_b32_e32 v55, 0xffff0000, v64
	v_lshlrev_b32_e32 v62, 16, v64
	v_mov_b32_e32 v82, v74
	v_mov_b32_e32 v83, v77
	v_mov_b32_e32 v93, v76
	v_lshlrev_b32_e32 v54, 16, v60
	v_pk_mul_f32 v[82:83], v[82:83], v[62:63]
	v_mov_b32_e32 v85, v76
	v_mov_b32_e32 v89, v63
	v_mov_b32_e32 v76, v75
	v_mov_b32_e32 v63, v55
	v_pk_fma_f32 v[82:83], v[92:93], v[54:55], v[82:83]
	v_mov_b32_e32 v84, v74
	v_mov_b32_e32 v88, v54
	v_pk_mul_f32 v[54:55], v[76:77], v[62:63]
	v_and_b32_e32 v63, 0xffff0000, v56
	v_and_b32_e32 v75, 0xffff0000, v52
	v_lshlrev_b32_e32 v74, 16, v56
	v_mov_b32_e32 v76, v78
	v_mov_b32_e32 v77, v81
	v_mov_b32_e32 v110, v79
	v_mov_b32_e32 v111, v80
	v_pk_fma_f32 v[54:55], v[84:85], v[88:89], v[54:55] neg_lo:[0,0,1] neg_hi:[0,0,1]
	v_lshlrev_b32_e32 v62, 16, v52
	v_pk_mul_f32 v[76:77], v[76:77], v[74:75]
	v_mov_b32_e32 v85, v80
	v_mov_b32_e32 v89, v75
	v_mov_b32_e32 v80, v79
	v_mov_b32_e32 v75, v63
	v_pk_fma_f32 v[76:77], v[110:111], v[62:63], v[76:77]
	v_mov_b32_e32 v84, v78
	v_mov_b32_e32 v88, v62
	v_pk_mul_f32 v[62:63], v[80:81], v[74:75]
; __device__ __forceinline__ float bfs(short h) { return __uint_as_float(((unsigned)(u16)h) << 16); }
; #define MFMA16(a, b, c) __builtin_amdgcn_mfma_f32_16x16x32_bf16(a, b, c, 0, 0, 0)
; __device__ __forceinline__ void phase_ret_o(PP p, const int g_wid, int layer) {
;     ...
;     bf16x8 qa[4];
;     {
;       int qpos = t0 + wid * 16 + fr;
;       if (qpos < L) {
;         const u16* qp = Pr + (long)(base + qpos) * 2048 + hd * 128 + fq * 8;
;         bf16x8 x0 = *reinterpret_cast<const bf16x8*>(qp), x1v = *reinterpret_cast<const bf16x8*>(qp + 32);
;         bf16x8 x2v = *reinterpret_cast<const bf16x8*>(qp + 64), x3 = *reinterpret_cast<const bf16x8*>(qp + 96);
;         const float2* cs = p->sincos + qpos * 64 + fq * 8;
;         float q0[8], q1[8], q2[8], q3[8];
; #pragma unroll
;         for (int i = 0; i < 8; ++i) {
;           float2 ca = cs[i], cb = cs[32 + i];
;           float a1 = bfs(x0[i]), a2 = bfs(x2v[i]);
;           q0[i] = a1 * ca.x - a2 * ca.y;
;           q2[i] = a2 * ca.x + a1 * ca.y;
;           float b1 = bfs(x1v[i]), b2 = bfs(x3[i]);
;           q1[i] = b1 * cb.x - b2 * cb.y;
;           q3[i] = b2 * cb.x + b1 * cb.y;
;         }
;         qa[0] = pack8(q0); qa[1] = pack8(q1); qa[2] = pack8(q2); qa[3] = pack8(q3);
;       } else {
; #pragma unroll
;         for (int k = 0; k < 4; ++k)
; #pragma unroll
;           for (int i = 0; i < 8; ++i) qa[k][i] = 0;
;       }
;     }
;     __syncthreads();
;     f32x4 sacc[8];
; #pragma unroll
;     for (int jt = 0; jt < 8; ++jt) {
;       sacc[jt] = f32x4{0.f, 0.f, 0.f, 0.f};
; #pragma unroll
;       for (int ks = 0; ks < 4; ++ks) {
;         bf16x8 b = *reinterpret_cast<const bf16x8*>(Ks + (jt * 16 + fr) * 136 + ks * 32 + fq * 8);
;         sacc[jt] = MFMA16(qa[ks], b, sacc[jt]);
;       }
;     }
	v_lshlrev_b32_e32 v60, 16, v65
	v_pk_fma_f32 v[74:75], v[84:85], v[88:89], v[62:63] neg_lo:[0,0,1] neg_hi:[0,0,1]
	v_and_b32_e32 v63, 0xffff0000, v65
	v_lshlrev_b32_e32 v62, 16, v61
	v_and_b32_e32 v61, 0xffff0000, v61
	v_mov_b32_e32 v64, v66
	v_mov_b32_e32 v65, v69
	v_mov_b32_e32 v91, v68
	v_pk_mul_f32 v[64:65], v[64:65], v[60:61]
	v_mov_b32_e32 v80, v62
	v_pk_fma_f32 v[78:79], v[90:91], v[62:63], v[64:65]
	v_mov_b32_e32 v65, v68
	v_mov_b32_e32 v81, v61
	v_mov_b32_e32 v68, v67
	v_mov_b32_e32 v61, v63
	v_and_b32_e32 v63, 0xffff0000, v57
	v_lshlrev_b32_e32 v62, 16, v53
	v_and_b32_e32 v53, 0xffff0000, v53
	v_lshlrev_b32_e32 v52, 16, v57
	v_mov_b32_e32 v56, v70
	v_mov_b32_e32 v57, v73
	v_mov_b32_e32 v108, v71
	v_mov_b32_e32 v109, v72
	v_mov_b32_e32 v64, v66
	v_pk_mul_f32 v[60:61], v[68:69], v[60:61]
	v_pk_mul_f32 v[56:57], v[56:57], v[52:53]
	v_pk_fma_f32 v[60:61], v[64:65], v[80:81], v[60:61] neg_lo:[0,0,1] neg_hi:[0,0,1]
	v_pk_fma_f32 v[66:67], v[108:109], v[62:63], v[56:57]
	v_mov_b32_e32 v57, v72
	v_mov_b32_e32 v65, v53
	v_mov_b32_e32 v72, v71
	v_mov_b32_e32 v53, v63
	v_mov_b32_e32 v56, v70
	v_mov_b32_e32 v64, v62
	v_pk_mul_f32 v[52:53], v[72:73], v[52:53]
	v_pk_fma_f32 v[120:121], v[194:195], v[198:199], v[120:121] neg_lo:[0,0,1] neg_hi:[0,0,1]
	v_pk_fma_f32 v[52:53], v[56:57], v[64:65], v[52:53] neg_lo:[0,0,1] neg_hi:[0,0,1]
	v_cvt_pk_bf16_f32 v62, v114, v115
	v_cvt_pk_bf16_f32 v63, v58, v59
	v_cvt_pk_bf16_f32 v64, v54, v55
	v_cvt_pk_bf16_f32 v65, v60, v61
	v_cvt_pk_bf16_f32 v58, v120, v121
	v_cvt_pk_bf16_f32 v59, v50, v51
	v_cvt_pk_bf16_f32 v60, v74, v75
	v_cvt_pk_bf16_f32 v61, v52, v53
	v_cvt_pk_bf16_f32 v54, v112, v113
	v_cvt_pk_bf16_f32 v55, v122, v123
	v_cvt_pk_bf16_f32 v56, v82, v83
	v_cvt_pk_bf16_f32 v57, v78, v79
	v_cvt_pk_bf16_f32 v50, v118, v119
	v_cvt_pk_bf16_f32 v51, v86, v87
	v_cvt_pk_bf16_f32 v52, v76, v77
	v_cvt_pk_bf16_f32 v53, v66, v67
.LBB0_199:
	s_or_b64 exec, exec, s[6:7]
	v_sub_u32_e32 v205, v130, v129
	v_sub_u32_e32 v205, v205, v125
	v_mul_u32_u24_e32 v206, 0x110, v203
	v_add_u32_e32 v205, v205, v206
	v_lshl_add_u32 v205, v204, 1, v205
	ds_write_b128 v205, v[62:65]
	ds_write_b128 v205, v[58:61] offset:64
	ds_write_b128 v205, v[54:57] offset:128
	ds_write_b128 v205, v[50:53] offset:192
	ds_read_b128 v[62:65], v130
	ds_read_b128 v[58:61], v130 offset:64
	ds_read_b128 v[54:57], v130 offset:128
	ds_read_b128 v[50:53], v130 offset:192
	s_waitcnt lgkmcnt(0)
	v_add_f32_e32 v0, v186, v187
	v_sub_f32_e32 v66, v0, v186
	v_sub_f32_e32 v78, v187, v66
	v_mul_f32_e32 v66, v183, v184
	v_mul_f32_e32 v66, v66, v185
	v_add_f32_e32 v70, v188, v66
	v_sub_f32_e32 v67, v70, v188
	v_add_u32_e32 v109, v125, v129
	v_sub_f32_e32 v71, v66, v67
	s_waitcnt lgkmcnt(0)
	s_barrier
	ds_read_b128 v[66:69], v109
	v_add_f32_e32 v74, v175, v71
	v_add_f32_e32 v79, v70, v74
	v_sub_f32_e32 v75, v79, v70
	ds_read_b128 v[70:73], v109 offset:64
	s_waitcnt lgkmcnt(1)
	v_mfma_f32_16x16x32_bf16 v[66:69], v[62:65], v[66:69], 0
	v_sub_f32_e32 v80, v74, v75
	ds_read_b128 v[74:77], v109 offset:128
	v_add_f32_e32 v81, v0, v79
	s_waitcnt lgkmcnt(1)
	v_mfma_f32_16x16x32_bf16 v[66:69], v[58:61], v[70:73], v[66:69]
	ds_read_b128 v[70:73], v109 offset:192
	v_sub_f32_e32 v82, v81, v0
	v_sub_f32_e32 v83, v81, v82
	s_waitcnt lgkmcnt(1)
	v_mfma_f32_16x16x32_bf16 v[66:69], v[54:57], v[74:77], v[66:69]
	ds_read_b128 v[74:77], v109 offset:4352
	v_sub_f32_e32 v0, v0, v83
	v_sub_f32_e32 v79, v79, v82
	s_waitcnt lgkmcnt(1)
	v_mfma_f32_16x16x32_bf16 v[110:113], v[50:53], v[70:73], v[66:69]
	v_add_f32_e32 v0, v79, v0
	v_add_f32_e32 v79, v78, v80
	v_sub_f32_e32 v82, v79, v78
	ds_read_b128 v[66:69], v109 offset:4416
	s_waitcnt lgkmcnt(1)
	v_mfma_f32_16x16x32_bf16 v[70:73], v[62:65], v[74:77], 0
	ds_read_b128 v[74:77], v109 offset:4480
	v_add_f32_e32 v0, v79, v0
	v_sub_f32_e32 v83, v79, v82
	s_waitcnt lgkmcnt(1)
	v_mfma_f32_16x16x32_bf16 v[66:69], v[58:61], v[66:69], v[70:73]
	v_add_f32_e32 v108, v81, v0
	v_sub_f32_e32 v78, v78, v83
	v_sub_f32_e32 v80, v80, v82
	ds_read_b128 v[70:73], v109 offset:4544
	s_waitcnt lgkmcnt(1)
	v_mfma_f32_16x16x32_bf16 v[66:69], v[54:57], v[74:77], v[66:69]
	ds_read_b128 v[74:77], v109 offset:8704
	v_sub_f32_e32 v79, v108, v81
	v_add_f32_e32 v78, v80, v78
	s_waitcnt lgkmcnt(1)
	v_mfma_f32_16x16x32_bf16 v[90:93], v[50:53], v[70:73], v[66:69]
	v_sub_f32_e32 v0, v0, v79
	v_add_f32_e32 v0, v78, v0
	v_add_f32_e32 v78, v182, v181
	ds_read_b128 v[66:69], v109 offset:8768
	s_waitcnt lgkmcnt(1)
	v_mfma_f32_16x16x32_bf16 v[70:73], v[62:65], v[74:77], 0
	ds_read_b128 v[74:77], v109 offset:8832
	v_sub_f32_e32 v79, v78, v182
	v_sub_f32_e32 v114, v181, v79
	s_waitcnt lgkmcnt(1)
	v_mfma_f32_16x16x32_bf16 v[66:69], v[58:61], v[66:69], v[70:73]
	v_mul_f32_e32 v79, v176, v179
	v_mul_f32_e32 v79, v79, v178
	v_add_f32_e32 v80, v180, v79
	ds_read_b128 v[70:73], v109 offset:8896
	s_waitcnt lgkmcnt(1)
	v_mfma_f32_16x16x32_bf16 v[66:69], v[54:57], v[74:77], v[66:69]
	ds_read_b128 v[74:77], v109 offset:13056
	v_add_f32_e32 v0, v108, v0
	v_cmp_nlt_f32_e32 vcc, 1.0, v170
	s_waitcnt lgkmcnt(1)
	v_mfma_f32_16x16x32_bf16 v[86:89], v[50:53], v[70:73], v[66:69]
	s_mov_b32 s6, 0x33800000
	v_cndmask_b32_e32 v0, v153, v0, vcc
	v_cmp_neq_f32_e32 vcc, 1.0, v170
	ds_read_b128 v[66:69], v109 offset:13120
	s_waitcnt lgkmcnt(1)
	v_mfma_f32_16x16x32_bf16 v[70:73], v[62:65], v[74:77], 0
	v_sub_f32_e32 v74, v80, v180
	v_sub_f32_e32 v79, v79, v74
	ds_read_b128 v[74:77], v109 offset:13184
	s_waitcnt lgkmcnt(1)
	v_mfma_f32_16x16x32_bf16 v[66:69], v[58:61], v[66:69], v[70:73]
	v_add_f32_e32 v79, v177, v79
	v_add_f32_e32 v81, v80, v79
	v_add_f32_e32 v116, v78, v81
	ds_read_b128 v[70:73], v109 offset:13248
	s_waitcnt lgkmcnt(1)
; #define MFMA16(a, b, c) __builtin_amdgcn_mfma_f32_16x16x32_bf16(a, b, c, 0, 0, 0)
; __device__ __forceinline__ void phase_ret_o(PP p, const int g_wid, int layer) {
;     ...
;     f32x4 sacc[8];
; #pragma unroll
;     for (int jt = 0; jt < 8; ++jt) {
;       sacc[jt] = f32x4{0.f, 0.f, 0.f, 0.f};
; #pragma unroll
;       for (int ks = 0; ks < 4; ++ks) {
;         bf16x8 b = *reinterpret_cast<const bf16x8*>(Ks + (jt * 16 + fr) * 136 + ks * 32 + fq * 8);
;         sacc[jt] = MFMA16(qa[ks], b, sacc[jt]);
;       }
;     }
;     int dbase = wid * 16 + fq * 4 - fr; asm volatile("" : "+v"(dbase));
; #pragma unroll
;     for (int jt = 0; jt < 8; ++jt)
; #pragma unroll
;       for (int r = 0; r < 4; ++r) {
;         const int j = jt * 16 + fr;
;         const int d = dbase + r - jt * 16;
;         float dec = d >= 0 ? __expf(lgf * (float)d) : __expf(lgb * (float)(-d));
;         Pw[(fq * 4 + r) * 136 + j] = f2bf(sacc[jt][r] * dec);
;       }
	v_mfma_f32_16x16x32_bf16 v[66:69], v[54:57], v[74:77], v[66:69]
	v_sub_f32_e32 v74, v81, v80
	v_sub_f32_e32 v115, v79, v74
	ds_read_b128 v[74:77], v109 offset:17408
	s_waitcnt lgkmcnt(1)
	v_mfma_f32_16x16x32_bf16 v[82:85], v[50:53], v[70:73], v[66:69]
	v_sub_f32_e32 v79, v116, v78
	v_add_f32_e32 v118, v114, v115
	v_sub_f32_e32 v119, v118, v114
	ds_read_b128 v[66:69], v109 offset:17472
	s_waitcnt lgkmcnt(1)
	v_mfma_f32_16x16x32_bf16 v[70:73], v[62:65], v[74:77], 0
	v_sub_f32_e32 v74, v116, v79
	v_sub_f32_e32 v78, v78, v74
	ds_read_b128 v[74:77], v109 offset:17536
	s_waitcnt lgkmcnt(1)
	v_mfma_f32_16x16x32_bf16 v[66:69], v[58:61], v[66:69], v[70:73]
	v_cndmask_b32_e32 v0, v154, v0, vcc
	v_cmp_gt_f32_e32 vcc, s6, v173
	s_nop 0
	v_sub_f32_e32 v70, v81, v79
	v_add_f32_e32 v117, v70, v78
	ds_read_b128 v[70:73], v109 offset:17600
	s_waitcnt lgkmcnt(1)
	v_mfma_f32_16x16x32_bf16 v[66:69], v[54:57], v[74:77], v[66:69]
	ds_read_b128 v[74:77], v109 offset:21760
	v_cndmask_b32_e32 v0, v0, v171, vcc
	v_cmp_nlt_f32_e32 vcc, 1.0, v169
	s_waitcnt lgkmcnt(1)
	v_mfma_f32_16x16x32_bf16 v[78:81], v[50:53], v[70:73], v[66:69]
	s_nop 2
	v_sub_f32_e32 v66, v118, v119
	v_sub_f32_e32 v114, v114, v66
	ds_read_b128 v[66:69], v109 offset:21824
	s_waitcnt lgkmcnt(1)
	v_mfma_f32_16x16x32_bf16 v[70:73], v[62:65], v[74:77], 0
	v_sub_f32_e32 v74, v115, v119
	v_add_f32_e32 v119, v74, v114
	ds_read_b128 v[74:77], v109 offset:21888
	s_waitcnt lgkmcnt(1)
	v_mfma_f32_16x16x32_bf16 v[66:69], v[58:61], v[66:69], v[70:73]
	v_add_f32_e32 v114, v118, v117
	v_add_f32_e32 v118, v116, v114
	s_nop 0
	ds_read_b128 v[70:73], v109 offset:21952
	s_waitcnt lgkmcnt(1)
	v_mfma_f32_16x16x32_bf16 v[66:69], v[54:57], v[74:77], v[66:69]
	v_sub_f32_e32 v74, v118, v116
	v_sub_f32_e32 v120, v114, v74
	ds_read_b128 v[114:117], v109 offset:26112
	s_waitcnt lgkmcnt(1)
	v_mfma_f32_16x16x32_bf16 v[74:77], v[50:53], v[70:73], v[66:69]
	v_add_f32_e32 v119, v119, v120
	v_add_f32_e32 v108, v118, v119
	v_cndmask_b32_e32 v108, v153, v108, vcc
	ds_read_b128 v[66:69], v109 offset:26176
	s_waitcnt lgkmcnt(1)
	v_mfma_f32_16x16x32_bf16 v[70:73], v[62:65], v[114:117], 0
	ds_read_b128 v[114:117], v109 offset:26240
	v_cmp_neq_f32_e32 vcc, 1.0, v169
	s_waitcnt lgkmcnt(1)
	v_mfma_f32_16x16x32_bf16 v[66:69], v[58:61], v[66:69], v[70:73]
	v_cndmask_b32_e32 v108, v154, v108, vcc
	v_cmp_gt_f32_e32 vcc, s6, v174
	s_nop 1
	ds_read_b128 v[70:73], v109 offset:26304
	s_waitcnt lgkmcnt(1)
	v_mfma_f32_16x16x32_bf16 v[66:69], v[54:57], v[114:117], v[66:69]
	ds_read_b128 v[114:117], v109 offset:30464
	v_cndmask_b32_e32 v108, v108, v172, vcc
	s_waitcnt lgkmcnt(1)
	v_mfma_f32_16x16x32_bf16 v[70:73], v[50:53], v[70:73], v[66:69]
	s_nop 3
	ds_read_b128 v[66:69], v109 offset:30528
	s_waitcnt lgkmcnt(1)
	v_mfma_f32_16x16x32_bf16 v[114:117], v[62:65], v[114:117], 0
	s_waitcnt lgkmcnt(0)
	v_mfma_f32_16x16x32_bf16 v[66:69], v[58:61], v[66:69], v[114:117]
	s_nop 5
	ds_read_b128 v[114:117], v109 offset:30592
	ds_read_b128 v[118:121], v109 offset:30656
	v_mov_b32_e32 v109, v126
	s_waitcnt lgkmcnt(1)
	v_mfma_f32_16x16x32_bf16 v[66:69], v[54:57], v[114:117], v[66:69]
	v_sub_u32_e32 v122, 0, v109
	v_max_i32_e32 v122, v109, v122
	v_cvt_f32_u32_e32 v122, v122
	v_cmp_gt_i32_e32 vcc, 0, v109
	v_add_u32_e32 v115, 1, v109
	v_not_b32_e32 v116, v109
	v_cndmask_b32_e32 v114, v0, v108, vcc
	v_mul_f32_e32 v114, v114, v122
	v_mul_f32_e32 v114, 0x3fb8aa3b, v114
	v_cmp_lt_i32_e32 vcc, -1, v115
	v_exp_f32_e32 v114, v114
	s_waitcnt lgkmcnt(0)
	v_mfma_f32_16x16x32_bf16 v[66:69], v[50:53], v[118:121], v[66:69]
	v_cndmask_b32_e32 v115, v116, v115, vcc
	v_cvt_f32_u32_e32 v115, v115
	v_mul_f32_e32 v110, v110, v114
	v_cndmask_b32_e32 v114, v108, v0, vcc
	v_mul_f32_e32 v114, v114, v115
	v_mul_f32_e32 v114, 0x3fb8aa3b, v114
	v_exp_f32_e32 v114, v114
	v_bfe_u32 v115, v110, 16, 1
	v_add3_u32 v110, v110, v115, s33
	ds_write_b16_d16_hi v95, v110
	v_mul_f32_e32 v110, v111, v114
	v_add_u32_e32 v111, 2, v109
	v_sub_u32_e32 v114, -2, v109
	v_cmp_lt_i32_e32 vcc, -1, v111
	v_sub_u32_e32 v115, -3, v109
	s_nop 0
	v_cndmask_b32_e32 v111, v114, v111, vcc
	v_cvt_f32_u32_e32 v111, v111
	v_bfe_u32 v114, v110, 16, 1
	v_add3_u32 v110, v110, v114, s33
	v_cndmask_b32_e32 v114, v108, v0, vcc
	v_mul_f32_e32 v111, v114, v111
	v_add_u32_e32 v114, 3, v109
	v_mul_f32_e32 v111, 0x3fb8aa3b, v111
	v_cmp_lt_i32_e32 vcc, -1, v114
	v_exp_f32_e32 v111, v111
	ds_write_b16_d16_hi v95, v110 offset:272
	v_cndmask_b32_e32 v114, v115, v114, vcc
	v_cvt_f32_u32_e32 v114, v114
	v_mul_f32_e32 v110, v112, v111
	v_cndmask_b32_e32 v111, v108, v0, vcc
	v_bfe_u32 v112, v110, 16, 1
	v_mul_f32_e32 v111, v111, v114
	v_mul_f32_e32 v111, 0x3fb8aa3b, v111
	v_exp_f32_e32 v111, v111
	v_add3_u32 v110, v110, v112, s33
	ds_write_b16_d16_hi v95, v110 offset:544
	v_sub_u32_e32 v112, 16, v109
	v_mul_f32_e32 v110, v113, v111
	v_add_u32_e32 v111, -16, v109
	v_cmp_lt_i32_e32 vcc, -1, v111
	v_sub_u32_e32 v113, 15, v109
	s_nop 0
	v_cndmask_b32_e32 v111, v112, v111, vcc
	v_cvt_f32_u32_e32 v111, v111
	v_bfe_u32 v112, v110, 16, 1
	v_add3_u32 v110, v110, v112, s33
	v_cndmask_b32_e32 v112, v108, v0, vcc
	v_mul_f32_e32 v111, v112, v111
	v_add_u32_e32 v112, -15, v109
	v_cmp_lt_i32_e32 vcc, -1, v112
	v_mul_f32_e32 v111, 0x3fb8aa3b, v111
	v_exp_f32_e32 v111, v111
	v_cndmask_b32_e32 v112, v113, v112, vcc
	v_cvt_f32_u32_e32 v112, v112
	ds_write_b16_d16_hi v95, v110 offset:816
	v_cndmask_b32_e32 v110, v108, v0, vcc
	v_mul_f32_e32 v90, v90, v111
	v_mul_f32_e32 v110, v110, v112
	v_mul_f32_e32 v110, 0x3fb8aa3b, v110
	v_exp_f32_e32 v110, v110
	v_bfe_u32 v111, v90, 16, 1
	v_add3_u32 v90, v90, v111, s33
	ds_write_b16_d16_hi v95, v90 offset:32
; __device__ __forceinline__ void phase_ret_o(PP p, const int g_wid, int layer) {
;     ...
; #pragma unroll
;     for (int jt = 0; jt < 8; ++jt)
; #pragma unroll
;       for (int r = 0; r < 4; ++r) {
;         const int j = jt * 16 + fr;
;         const int d = dbase + r - jt * 16;
;         float dec = d >= 0 ? __expf(lgf * (float)d) : __expf(lgb * (float)(-d));
;         Pw[(fq * 4 + r) * 136 + j] = f2bf(sacc[jt][r] * dec);
;       }
	v_mul_f32_e32 v90, v91, v110
	v_add_u32_e32 v91, -14, v109
	v_sub_u32_e32 v110, 14, v109
	v_cmp_lt_i32_e32 vcc, -1, v91
	v_sub_u32_e32 v111, 13, v109
	s_nop 0
	v_cndmask_b32_e32 v91, v110, v91, vcc
	v_cvt_f32_u32_e32 v91, v91
	v_bfe_u32 v110, v90, 16, 1
	v_add3_u32 v90, v90, v110, s33
	v_cndmask_b32_e32 v110, v108, v0, vcc
	v_mul_f32_e32 v91, v110, v91
	v_add_u32_e32 v110, -13, v109
	v_mul_f32_e32 v91, 0x3fb8aa3b, v91
	v_cmp_lt_i32_e32 vcc, -1, v110
	v_exp_f32_e32 v91, v91
	ds_write_b16_d16_hi v95, v90 offset:304
	v_cndmask_b32_e32 v110, v111, v110, vcc
	v_cvt_f32_u32_e32 v110, v110
	v_mul_f32_e32 v90, v92, v91
	v_cndmask_b32_e32 v91, v108, v0, vcc
	v_bfe_u32 v92, v90, 16, 1
	v_mul_f32_e32 v91, v91, v110
	v_mul_f32_e32 v91, 0x3fb8aa3b, v91
	v_exp_f32_e32 v91, v91
	v_add3_u32 v90, v90, v92, s33
	ds_write_b16_d16_hi v95, v90 offset:576
	v_sub_u32_e32 v92, 32, v109
	v_mul_f32_e32 v90, v93, v91
	v_subrev_u32_e32 v91, 32, v109
	v_cmp_lt_i32_e32 vcc, -1, v91
	v_sub_u32_e32 v93, 31, v109
	s_nop 0
	v_cndmask_b32_e32 v91, v92, v91, vcc
	v_cvt_f32_u32_e32 v91, v91
	v_bfe_u32 v92, v90, 16, 1
	v_add3_u32 v90, v90, v92, s33
	v_cndmask_b32_e32 v92, v108, v0, vcc
	v_mul_f32_e32 v91, v92, v91
	v_subrev_u32_e32 v92, 31, v109
	v_cmp_lt_i32_e32 vcc, -1, v92
	v_mul_f32_e32 v91, 0x3fb8aa3b, v91
	v_exp_f32_e32 v91, v91
	v_cndmask_b32_e32 v92, v93, v92, vcc
	v_cvt_f32_u32_e32 v92, v92
	ds_write_b16_d16_hi v95, v90 offset:848
	v_cndmask_b32_e32 v90, v108, v0, vcc
	v_mul_f32_e32 v86, v86, v91
	v_mul_f32_e32 v90, v90, v92
	v_mul_f32_e32 v90, 0x3fb8aa3b, v90
	v_exp_f32_e32 v90, v90
	v_bfe_u32 v91, v86, 16, 1
	v_add3_u32 v86, v86, v91, s33
	ds_write_b16_d16_hi v95, v86 offset:64
	v_mul_f32_e32 v86, v87, v90
	v_subrev_u32_e32 v87, 30, v109
	v_sub_u32_e32 v90, 30, v109
	v_cmp_lt_i32_e32 vcc, -1, v87
	v_sub_u32_e32 v91, 29, v109
	s_nop 0
	v_cndmask_b32_e32 v87, v90, v87, vcc
	v_cvt_f32_u32_e32 v87, v87
	v_bfe_u32 v90, v86, 16, 1
	v_add3_u32 v86, v86, v90, s33
	v_cndmask_b32_e32 v90, v108, v0, vcc
	v_mul_f32_e32 v87, v90, v87
	v_subrev_u32_e32 v90, 29, v109
	v_mul_f32_e32 v87, 0x3fb8aa3b, v87
	v_cmp_lt_i32_e32 vcc, -1, v90
	v_exp_f32_e32 v87, v87
	ds_write_b16_d16_hi v95, v86 offset:336
	v_cndmask_b32_e32 v90, v91, v90, vcc
	v_cvt_f32_u32_e32 v90, v90
	v_mul_f32_e32 v86, v88, v87
	v_cndmask_b32_e32 v87, v108, v0, vcc
	v_bfe_u32 v88, v86, 16, 1
	v_mul_f32_e32 v87, v87, v90
	v_mul_f32_e32 v87, 0x3fb8aa3b, v87
	v_exp_f32_e32 v87, v87
	v_add3_u32 v86, v86, v88, s33
	ds_write_b16_d16_hi v95, v86 offset:608
	v_sub_u32_e32 v88, 48, v109
	v_mul_f32_e32 v86, v89, v87
	v_subrev_u32_e32 v87, 48, v109
	v_cmp_lt_i32_e32 vcc, -1, v87
	v_sub_u32_e32 v89, 47, v109
	s_nop 0
	v_cndmask_b32_e32 v87, v88, v87, vcc
	v_cvt_f32_u32_e32 v87, v87
	v_bfe_u32 v88, v86, 16, 1
	v_add3_u32 v86, v86, v88, s33
	v_cndmask_b32_e32 v88, v108, v0, vcc
	v_mul_f32_e32 v87, v88, v87
	v_subrev_u32_e32 v88, 47, v109
	v_cmp_lt_i32_e32 vcc, -1, v88
	v_mul_f32_e32 v87, 0x3fb8aa3b, v87
	v_exp_f32_e32 v87, v87
	v_cndmask_b32_e32 v88, v89, v88, vcc
	v_cvt_f32_u32_e32 v88, v88
	ds_write_b16_d16_hi v95, v86 offset:880
	v_cndmask_b32_e32 v86, v108, v0, vcc
	v_mul_f32_e32 v82, v82, v87
	v_mul_f32_e32 v86, v86, v88
	v_mul_f32_e32 v86, 0x3fb8aa3b, v86
	v_exp_f32_e32 v86, v86
	v_bfe_u32 v87, v82, 16, 1
	v_add3_u32 v82, v82, v87, s33
	ds_write_b16_d16_hi v95, v82 offset:96
	v_mul_f32_e32 v82, v83, v86
	v_subrev_u32_e32 v83, 46, v109
	v_sub_u32_e32 v86, 46, v109
	v_cmp_lt_i32_e32 vcc, -1, v83
	v_sub_u32_e32 v87, 45, v109
	s_nop 0
	v_cndmask_b32_e32 v83, v86, v83, vcc
	v_cvt_f32_u32_e32 v83, v83
	v_bfe_u32 v86, v82, 16, 1
	v_add3_u32 v82, v82, v86, s33
	v_cndmask_b32_e32 v86, v108, v0, vcc
	v_mul_f32_e32 v83, v86, v83
	v_subrev_u32_e32 v86, 45, v109
	v_mul_f32_e32 v83, 0x3fb8aa3b, v83
	v_cmp_lt_i32_e32 vcc, -1, v86
	v_exp_f32_e32 v83, v83
	ds_write_b16_d16_hi v95, v82 offset:368
	v_cndmask_b32_e32 v86, v87, v86, vcc
	v_cvt_f32_u32_e32 v86, v86
	v_mul_f32_e32 v82, v84, v83
	v_cndmask_b32_e32 v83, v108, v0, vcc
	v_bfe_u32 v84, v82, 16, 1
	v_mul_f32_e32 v83, v83, v86
	v_mul_f32_e32 v83, 0x3fb8aa3b, v83
	v_exp_f32_e32 v83, v83
	v_add3_u32 v82, v82, v84, s33
	ds_write_b16_d16_hi v95, v82 offset:640
	v_sub_u32_e32 v84, 64, v109
	v_mul_f32_e32 v82, v85, v83
	v_subrev_u32_e32 v83, 64, v109
	v_cmp_lt_i32_e32 vcc, -1, v83
	v_sub_u32_e32 v85, 63, v109
	s_nop 0
	v_cndmask_b32_e32 v83, v84, v83, vcc
	v_cvt_f32_u32_e32 v83, v83
	v_bfe_u32 v84, v82, 16, 1
	v_add3_u32 v82, v82, v84, s33
	v_cndmask_b32_e32 v84, v108, v0, vcc
	v_mul_f32_e32 v83, v84, v83
	v_subrev_u32_e32 v84, 63, v109
	v_cmp_lt_i32_e32 vcc, -1, v84
	v_mul_f32_e32 v83, 0x3fb8aa3b, v83
	v_exp_f32_e32 v83, v83
	v_cndmask_b32_e32 v84, v85, v84, vcc
	v_cvt_f32_u32_e32 v84, v84
	ds_write_b16_d16_hi v95, v82 offset:912
	v_cndmask_b32_e32 v82, v108, v0, vcc
	v_mul_f32_e32 v78, v78, v83
	v_mul_f32_e32 v82, v82, v84
	v_mul_f32_e32 v82, 0x3fb8aa3b, v82
	v_exp_f32_e32 v82, v82
	v_bfe_u32 v83, v78, 16, 1
	v_add3_u32 v78, v78, v83, s33
	ds_write_b16_d16_hi v95, v78 offset:128
	v_mul_f32_e32 v78, v79, v82
	v_subrev_u32_e32 v79, 62, v109
	v_sub_u32_e32 v82, 62, v109
	v_cmp_lt_i32_e32 vcc, -1, v79
	v_sub_u32_e32 v83, 61, v109
	s_nop 0
	v_cndmask_b32_e32 v79, v82, v79, vcc
	v_cvt_f32_u32_e32 v79, v79
	v_bfe_u32 v82, v78, 16, 1
	v_add3_u32 v78, v78, v82, s33
	v_cndmask_b32_e32 v82, v108, v0, vcc
	v_mul_f32_e32 v79, v82, v79
	v_subrev_u32_e32 v82, 61, v109
	v_mul_f32_e32 v79, 0x3fb8aa3b, v79
	v_cmp_lt_i32_e32 vcc, -1, v82
	v_exp_f32_e32 v79, v79
	ds_write_b16_d16_hi v95, v78 offset:400
	v_cndmask_b32_e32 v82, v83, v82, vcc
	v_cvt_f32_u32_e32 v82, v82
	v_mul_f32_e32 v78, v80, v79
; __device__ __forceinline__ void phase_ret_o(PP p, const int g_wid, int layer) {
;     ...
; #pragma unroll
;     for (int jt = 0; jt < 8; ++jt)
; #pragma unroll
;       for (int r = 0; r < 4; ++r) {
;         const int j = jt * 16 + fr;
;         const int d = dbase + r - jt * 16;
;         float dec = d >= 0 ? __expf(lgf * (float)d) : __expf(lgb * (float)(-d));
;         Pw[(fq * 4 + r) * 136 + j] = f2bf(sacc[jt][r] * dec);
;       }
;     __syncthreads();
	v_cndmask_b32_e32 v79, v108, v0, vcc
	v_bfe_u32 v80, v78, 16, 1
	v_mul_f32_e32 v79, v79, v82
	v_mul_f32_e32 v79, 0x3fb8aa3b, v79
	v_exp_f32_e32 v79, v79
	v_add3_u32 v78, v78, v80, s33
	ds_write_b16_d16_hi v95, v78 offset:672
	v_sub_u32_e32 v80, 0x50, v109
	v_mul_f32_e32 v78, v81, v79
	v_add_u32_e32 v79, 0xffffffb0, v109
	v_cmp_lt_i32_e32 vcc, -1, v79
	v_sub_u32_e32 v81, 0x4f, v109
	s_nop 0
	v_cndmask_b32_e32 v79, v80, v79, vcc
	v_cvt_f32_u32_e32 v79, v79
	v_bfe_u32 v80, v78, 16, 1
	v_add3_u32 v78, v78, v80, s33
	v_cndmask_b32_e32 v80, v108, v0, vcc
	v_mul_f32_e32 v79, v80, v79
	v_add_u32_e32 v80, 0xffffffb1, v109
	v_cmp_lt_i32_e32 vcc, -1, v80
	v_mul_f32_e32 v79, 0x3fb8aa3b, v79
	v_exp_f32_e32 v79, v79
	v_cndmask_b32_e32 v80, v81, v80, vcc
	v_cvt_f32_u32_e32 v80, v80
	ds_write_b16_d16_hi v95, v78 offset:944
	v_cndmask_b32_e32 v78, v108, v0, vcc
	v_mul_f32_e32 v74, v74, v79
	v_mul_f32_e32 v78, v78, v80
	v_mul_f32_e32 v78, 0x3fb8aa3b, v78
	v_exp_f32_e32 v78, v78
	v_bfe_u32 v79, v74, 16, 1
	v_add3_u32 v74, v74, v79, s33
	ds_write_b16_d16_hi v95, v74 offset:160
	v_mul_f32_e32 v74, v75, v78
	v_add_u32_e32 v75, 0xffffffb2, v109
	v_sub_u32_e32 v78, 0x4e, v109
	v_cmp_lt_i32_e32 vcc, -1, v75
	v_sub_u32_e32 v79, 0x4d, v109
	s_nop 0
	v_cndmask_b32_e32 v75, v78, v75, vcc
	v_cvt_f32_u32_e32 v75, v75
	v_bfe_u32 v78, v74, 16, 1
	v_add3_u32 v74, v74, v78, s33
	v_cndmask_b32_e32 v78, v108, v0, vcc
	v_mul_f32_e32 v75, v78, v75
	v_add_u32_e32 v78, 0xffffffb3, v109
	v_mul_f32_e32 v75, 0x3fb8aa3b, v75
	v_cmp_lt_i32_e32 vcc, -1, v78
	v_exp_f32_e32 v75, v75
	ds_write_b16_d16_hi v95, v74 offset:432
	v_cndmask_b32_e32 v78, v79, v78, vcc
	v_cvt_f32_u32_e32 v78, v78
	v_mul_f32_e32 v74, v76, v75
	v_cndmask_b32_e32 v75, v108, v0, vcc
	v_bfe_u32 v76, v74, 16, 1
	v_mul_f32_e32 v75, v75, v78
	v_mul_f32_e32 v75, 0x3fb8aa3b, v75
	v_exp_f32_e32 v75, v75
	v_add3_u32 v74, v74, v76, s33
	ds_write_b16_d16_hi v95, v74 offset:704
	v_sub_u32_e32 v76, 0x60, v109
	v_mul_f32_e32 v74, v77, v75
	v_add_u32_e32 v75, 0xffffffa0, v109
	v_cmp_lt_i32_e32 vcc, -1, v75
	v_sub_u32_e32 v77, 0x5f, v109
	s_nop 0
	v_cndmask_b32_e32 v75, v76, v75, vcc
	v_cvt_f32_u32_e32 v75, v75
	v_bfe_u32 v76, v74, 16, 1
	v_add3_u32 v74, v74, v76, s33
	v_cndmask_b32_e32 v76, v108, v0, vcc
	v_mul_f32_e32 v75, v76, v75
	v_add_u32_e32 v76, 0xffffffa1, v109
	v_cmp_lt_i32_e32 vcc, -1, v76
	v_mul_f32_e32 v75, 0x3fb8aa3b, v75
	v_exp_f32_e32 v75, v75
	v_cndmask_b32_e32 v76, v77, v76, vcc
	v_cvt_f32_u32_e32 v76, v76
	ds_write_b16_d16_hi v95, v74 offset:976
	v_cndmask_b32_e32 v74, v108, v0, vcc
	v_mul_f32_e32 v70, v70, v75
	v_mul_f32_e32 v74, v74, v76
	v_mul_f32_e32 v74, 0x3fb8aa3b, v74
	v_exp_f32_e32 v74, v74
	v_bfe_u32 v75, v70, 16, 1
	v_add3_u32 v70, v70, v75, s33
	ds_write_b16_d16_hi v95, v70 offset:192
	v_mul_f32_e32 v70, v71, v74
	v_add_u32_e32 v71, 0xffffffa2, v109
	v_sub_u32_e32 v74, 0x5e, v109
	v_cmp_lt_i32_e32 vcc, -1, v71
	v_sub_u32_e32 v75, 0x5d, v109
	s_nop 0
	v_cndmask_b32_e32 v71, v74, v71, vcc
	v_cvt_f32_u32_e32 v71, v71
	v_bfe_u32 v74, v70, 16, 1
	v_add3_u32 v70, v70, v74, s33
	v_cndmask_b32_e32 v74, v108, v0, vcc
	v_mul_f32_e32 v71, v74, v71
	v_add_u32_e32 v74, 0xffffffa3, v109
	v_mul_f32_e32 v71, 0x3fb8aa3b, v71
	v_cmp_lt_i32_e32 vcc, -1, v74
	v_exp_f32_e32 v71, v71
	ds_write_b16_d16_hi v95, v70 offset:464
	v_cndmask_b32_e32 v74, v75, v74, vcc
	v_cvt_f32_u32_e32 v74, v74
	v_mul_f32_e32 v70, v72, v71
	v_cndmask_b32_e32 v71, v108, v0, vcc
	v_bfe_u32 v72, v70, 16, 1
	v_mul_f32_e32 v71, v71, v74
	v_mul_f32_e32 v71, 0x3fb8aa3b, v71
	v_exp_f32_e32 v71, v71
	v_add3_u32 v70, v70, v72, s33
	ds_write_b16_d16_hi v95, v70 offset:736
	v_sub_u32_e32 v72, 0x70, v109
	v_mul_f32_e32 v70, v73, v71
	v_add_u32_e32 v71, 0xffffff90, v109
	v_cmp_lt_i32_e32 vcc, -1, v71
	v_sub_u32_e32 v73, 0x6f, v109
	s_nop 0
	v_cndmask_b32_e32 v71, v72, v71, vcc
	v_cvt_f32_u32_e32 v71, v71
	v_bfe_u32 v72, v70, 16, 1
	v_add3_u32 v70, v70, v72, s33
	v_cndmask_b32_e32 v72, v108, v0, vcc
	v_mul_f32_e32 v71, v72, v71
	v_add_u32_e32 v72, 0xffffff91, v109
	v_cmp_lt_i32_e32 vcc, -1, v72
	v_mul_f32_e32 v71, 0x3fb8aa3b, v71
	v_exp_f32_e32 v71, v71
	v_cndmask_b32_e32 v72, v73, v72, vcc
	v_cvt_f32_u32_e32 v72, v72
	ds_write_b16_d16_hi v95, v70 offset:1008
	v_cndmask_b32_e32 v70, v108, v0, vcc
	v_mul_f32_e32 v66, v66, v71
	v_mul_f32_e32 v70, v70, v72
	v_mul_f32_e32 v70, 0x3fb8aa3b, v70
	v_exp_f32_e32 v70, v70
	v_bfe_u32 v71, v66, 16, 1
	v_add3_u32 v66, v66, v71, s33
	ds_write_b16_d16_hi v95, v66 offset:224
	v_mul_f32_e32 v66, v67, v70
	v_add_u32_e32 v67, 0xffffff92, v109
	v_sub_u32_e32 v70, 0x6e, v109
	v_cmp_lt_i32_e32 vcc, -1, v67
	v_sub_u32_e32 v71, 0x6d, v109
	s_nop 0
	v_cndmask_b32_e32 v67, v70, v67, vcc
	v_cvt_f32_u32_e32 v67, v67
	v_bfe_u32 v70, v66, 16, 1
	v_add3_u32 v66, v66, v70, s33
	v_cndmask_b32_e32 v70, v108, v0, vcc
	v_mul_f32_e32 v67, v70, v67
	v_add_u32_e32 v70, 0xffffff93, v109
	v_mul_f32_e32 v67, 0x3fb8aa3b, v67
	v_cmp_lt_i32_e32 vcc, -1, v70
	v_exp_f32_e32 v67, v67
	ds_write_b16_d16_hi v95, v66 offset:496
	v_cndmask_b32_e32 v70, v71, v70, vcc
	v_cvt_f32_u32_e32 v70, v70
	v_mul_f32_e32 v66, v68, v67
	v_cndmask_b32_e32 v67, v108, v0, vcc
	v_bfe_u32 v68, v66, 16, 1
	v_mul_f32_e32 v67, v67, v70
	v_mul_f32_e32 v67, 0x3fb8aa3b, v67
	v_exp_f32_e32 v67, v67
	v_add3_u32 v66, v66, v68, s33
	ds_write_b16_d16_hi v95, v66 offset:768
	v_mul_f32_e32 v0, v0, v127
	v_mul_f32_e32 v66, v69, v67
	v_bfe_u32 v67, v66, 16, 1
	v_add3_u32 v66, v66, v67, s33
	ds_write_b16_d16_hi v95, v66 offset:1040
	s_waitcnt lgkmcnt(0)
	s_barrier
; __device__ __forceinline__ float bfs(short h) { return __uint_as_float(((unsigned)(u16)h) << 16); }
; #define MFMA16(a, b, c) __builtin_amdgcn_mfma_f32_16x16x32_bf16(a, b, c, 0, 0, 0)
; __device__ __forceinline__ void phase_ret_o(PP p, const int g_wid, int layer) {
;     ...
; #pragma unroll
;     for (int i = 0; i < 4; ++i) {
;       const int c = tid + 512 * i, e_ = c >> 4, d0 = (c & 15) * 8;
;       *reinterpret_cast<bf16x8*>(Ks + e_ * 136 + d0) = pf[i];
;       *reinterpret_cast<bf16x8*>(Sbl + e_ * 136 + d0) = pb[i];
;     }
;     __syncthreads();
;     f32x4 o1[8];
; #pragma unroll
;     for (int et = 0; et < 8; ++et) o1[et] = f32x4{0.f, 0.f, 0.f, 0.f};
;     bf16x8 qf[4], qb[4];
;     {
;       const int ia = wid * 16 + fr;
;       const float df = __expf(lgf * (float)(ia + 1)), db = __expf(lgb * (float)(128 - ia));
; #pragma unroll
;       for (int ks = 0; ks < 4; ++ks) {
;         float tf[8], tb[8];
; #pragma unroll
;         for (int i = 0; i < 8; ++i) {
;           float qv = bfs(qa[ks][i]);
;           tf[i] = qv * df;
;           tb[i] = qv * db;
;         }
;         qf[ks] = pack8(tf); qb[ks] = pack8(tb);
;       }
;     }
; #pragma unroll
;     for (int ks = 0; ks < 4; ++ks) {
;       bf16x8 a = *reinterpret_cast<const bf16x8*>(Pw + fr * 136 + ks * 32 + fq * 8);
; #pragma unroll
;       for (int et = 0; et < 8; ++et) {
;         bf16x8 b = tr_frag(Vs + (ks * 32) * 136 + et * 16, 136, lane);
;         o1[et] = MFMA16(a, b, o1[et]);
;         bf16x8 bf = *reinterpret_cast<const bf16x8*>(Ks + (et * 16 + fr) * 136 + ks * 32 + fq * 8);
;         o1[et] = MFMA16(qf[ks], bf, o1[et]);
;         bf16x8 bb = *reinterpret_cast<const bf16x8*>(Sbl + (et * 16 + fr) * 136 + ks * 32 + fq * 8);
;         o1[et] = MFMA16(qb[ks], bb, o1[et]);
;       }
	ds_write_b128 v134, v[18:21]
	ds_write_b128 v135, v[22:25]
	ds_write_b128 v136, v[26:29]
	ds_write_b128 v137, v[30:33]
	ds_write_b128 v138, v[34:37]
	ds_write_b128 v139, v[38:41]
	ds_write_b128 v140, v[42:45]
	ds_write_b128 v141, v[46:49]
	v_mul_f32_e32 v18, 0x3fb8aa3b, v0
	v_mul_f32_e32 v0, v108, v128
	v_mul_f32_e32 v0, 0x3fb8aa3b, v0
	v_exp_f32_e32 v0, v0
	v_exp_f32_e32 v18, v18
	v_and_b32_e32 v21, 0xffff0000, v62
	v_lshlrev_b32_e32 v20, 16, v62
	v_and_b32_e32 v25, 0xffff0000, v63
	v_lshlrev_b32_e32 v24, 16, v63
	v_pk_mul_f32 v[22:23], v[0:1], v[20:21] op_sel_hi:[0,1]
	v_pk_mul_f32 v[20:21], v[18:19], v[20:21] op_sel_hi:[0,1]
	v_pk_mul_f32 v[26:27], v[0:1], v[24:25] op_sel_hi:[0,1]
	v_pk_mul_f32 v[24:25], v[18:19], v[24:25] op_sel_hi:[0,1]
	v_and_b32_e32 v33, 0xffff0000, v65
	v_lshlrev_b32_e32 v32, 16, v65
	v_cvt_pk_bf16_f32 v42, v20, v21
	v_cvt_pk_bf16_f32 v43, v24, v25
	v_and_b32_e32 v21, 0xffff0000, v58
	v_lshlrev_b32_e32 v20, 16, v58
	v_and_b32_e32 v25, 0xffff0000, v59
	v_lshlrev_b32_e32 v24, 16, v59
	v_pk_mul_f32 v[34:35], v[0:1], v[32:33] op_sel_hi:[0,1]
	v_cvt_pk_bf16_f32 v46, v22, v23
	v_cvt_pk_bf16_f32 v47, v26, v27
	v_pk_mul_f32 v[22:23], v[0:1], v[20:21] op_sel_hi:[0,1]
	v_pk_mul_f32 v[26:27], v[0:1], v[24:25] op_sel_hi:[0,1]
	v_pk_mul_f32 v[24:25], v[18:19], v[24:25] op_sel_hi:[0,1]
	s_waitcnt lgkmcnt(0)
	s_barrier
	v_cvt_pk_bf16_f32 v49, v34, v35
	v_cvt_pk_bf16_f32 v39, v24, v25
	v_cvt_pk_bf16_f32 v34, v22, v23
	ds_read_b128 v[22:25], v130
	v_and_b32_e32 v29, 0xffff0000, v64
	v_lshlrev_b32_e32 v28, 16, v64
	v_pk_mul_f32 v[30:31], v[0:1], v[28:29] op_sel_hi:[0,1]
	v_pk_mul_f32 v[28:29], v[18:19], v[28:29] op_sel_hi:[0,1]
	v_pk_mul_f32 v[32:33], v[18:19], v[32:33] op_sel_hi:[0,1]
	v_cvt_pk_bf16_f32 v44, v28, v29
	v_cvt_pk_bf16_f32 v45, v32, v33
	v_and_b32_e32 v29, 0xffff0000, v60
	v_lshlrev_b32_e32 v28, 16, v60
	v_and_b32_e32 v33, 0xffff0000, v61
	v_lshlrev_b32_e32 v32, 16, v61
	v_cvt_pk_bf16_f32 v48, v30, v31
	v_pk_mul_f32 v[30:31], v[0:1], v[28:29] op_sel_hi:[0,1]
	v_pk_mul_f32 v[28:29], v[18:19], v[28:29] op_sel_hi:[0,1]
	v_pk_mul_f32 v[58:59], v[0:1], v[32:33] op_sel_hi:[0,1]
	v_pk_mul_f32 v[32:33], v[18:19], v[32:33] op_sel_hi:[0,1]
	v_cvt_pk_bf16_f32 v40, v28, v29
	v_cvt_pk_bf16_f32 v41, v32, v33
	v_cvt_pk_bf16_f32 v35, v26, v27
	v_cvt_pk_bf16_f32 v36, v30, v31
	v_cvt_pk_bf16_f32 v37, v58, v59
	ds_read_b64_tr_b16 v[28:29], v131 offset:35904
	ds_read_b64_tr_b16 v[26:27], v131 offset:34816
	ds_read_b128 v[30:33], v142
	ds_read_b64_tr_b16 v[58:59], v131 offset:34976
	ds_read_b64_tr_b16 v[62:63], v131 offset:35008
	ds_read_b64_tr_b16 v[66:67], v131 offset:35040
	s_waitcnt lgkmcnt(4)
	v_mfma_f32_16x16x32_bf16 v[26:29], v[22:25], v[26:29], 0
	ds_read_b128 v[68:71], v143
	ds_read_b128 v[72:75], v142 offset:4352
	v_pk_mul_f32 v[20:21], v[18:19], v[20:21] op_sel_hi:[0,1]
	v_cvt_pk_bf16_f32 v38, v20, v21
	s_waitcnt lgkmcnt(5)
	v_mfma_f32_16x16x32_bf16 v[26:29], v[42:45], v[30:33], v[26:29]
	ds_read_b128 v[30:33], v142 offset:8704
	v_and_b32_e32 v21, 0xffff0000, v54
	v_lshlrev_b32_e32 v20, 16, v54
	s_waitcnt lgkmcnt(2)
	v_mfma_f32_16x16x32_bf16 v[78:81], v[46:49], v[68:71], v[26:29]
	s_nop 2
	ds_read_b64_tr_b16 v[28:29], v131 offset:35936
	ds_read_b64_tr_b16 v[26:27], v131 offset:34848
	ds_read_b64_tr_b16 v[68:69], v131 offset:34880
	ds_read_b64_tr_b16 v[82:83], v131 offset:34912
	ds_read_b64_tr_b16 v[86:87], v131 offset:34944
	ds_read_b64_tr_b16 v[70:71], v131 offset:35968
	ds_read_b64_tr_b16 v[84:85], v131 offset:36000
	ds_read_b64_tr_b16 v[88:89], v131 offset:36032
	ds_read_b128 v[90:93], v144
	v_and_b32_e32 v65, 0xffff0000, v55
	s_waitcnt lgkmcnt(7)
	v_mfma_f32_16x16x32_bf16 v[26:29], v[22:25], v[26:29], 0
	v_lshlrev_b32_e32 v64, 16, v55
	v_and_b32_e32 v55, 0xffff0000, v56
	v_lshlrev_b32_e32 v54, 16, v56
	v_mfma_f32_16x16x32_bf16 v[26:29], v[42:45], v[72:75], v[26:29]
	ds_read_b128 v[72:75], v145
	v_pk_mul_f32 v[108:109], v[0:1], v[54:55] op_sel_hi:[0,1]
	v_pk_mul_f32 v[110:111], v[18:19], v[54:55] op_sel_hi:[0,1]
	s_waitcnt lgkmcnt(1)
	v_mfma_f32_16x16x32_bf16 v[90:93], v[46:49], v[90:93], v[26:29]
	v_and_b32_e32 v55, 0xffff0000, v57
	v_lshlrev_b32_e32 v54, 16, v57
	v_pk_mul_f32 v[112:113], v[0:1], v[54:55] op_sel_hi:[0,1]
	v_mfma_f32_16x16x32_bf16 v[26:29], v[22:25], v[68:71], 0
	v_mul_f32_e64 v114, v18, v54
	v_mul_f32_e64 v115, v18, v55
	v_pk_mul_f32 v[60:61], v[0:1], v[20:21] op_sel_hi:[0,1]
	v_pk_mul_f32 v[76:77], v[0:1], v[64:65] op_sel_hi:[0,1]
	v_mfma_f32_16x16x32_bf16 v[26:29], v[42:45], v[30:33], v[26:29]
	v_mul_f32_e64 v64, v18, v64
	v_mul_f32_e64 v65, v18, v65
	v_cvt_pk_bf16_f32 v31, v64, v65
	v_pk_mul_f32 v[20:21], v[18:19], v[20:21] op_sel_hi:[0,1]
	s_waitcnt lgkmcnt(0)
	v_mfma_f32_16x16x32_bf16 v[54:57], v[46:49], v[72:75], v[26:29]
	ds_read_b128 v[72:75], v147
	v_cvt_pk_bf16_f32 v30, v20, v21
	v_cvt_pk_bf16_f32 v32, v110, v111
	ds_read_b128 v[26:29], v146
	v_mfma_f32_16x16x32_bf16 v[68:71], v[22:25], v[82:85], 0
	v_and_b32_e32 v21, 0xffff0000, v50
	v_lshlrev_b32_e32 v20, 16, v50
	v_and_b32_e32 v111, 0xffff0000, v51
	s_waitcnt lgkmcnt(0)
	v_mfma_f32_16x16x32_bf16 v[68:71], v[42:45], v[26:29], v[68:71]
	v_cvt_pk_bf16_f32 v26, v60, v61
	ds_read_b64_tr_b16 v[60:61], v131 offset:36064
	v_cvt_pk_bf16_f32 v27, v76, v77
	v_mfma_f32_16x16x32_bf16 v[82:85], v[46:49], v[72:75], v[68:71]
	v_lshlrev_b32_e32 v110, 16, v51
	v_and_b32_e32 v51, 0xffff0000, v52
	v_lshlrev_b32_e32 v50, 16, v52
	s_nop 0
	ds_read_b128 v[68:71], v159
	v_mfma_f32_16x16x32_bf16 v[72:75], v[22:25], v[86:89], 0
	ds_read_b128 v[86:89], v160
	v_cvt_pk_bf16_f32 v33, v114, v115
	v_and_b32_e32 v115, 0xffff0000, v53
	s_waitcnt lgkmcnt(1)
; __device__ __forceinline__ float bfs(short h) { return __uint_as_float(((unsigned)(u16)h) << 16); }
; #define MFMA16(a, b, c) __builtin_amdgcn_mfma_f32_16x16x32_bf16(a, b, c, 0, 0, 0)
; __device__ __forceinline__ void phase_ret_o(PP p, const int g_wid, int layer) {
;     ...
;     bf16x8 qf[4], qb[4];
;     {
;       const int ia = wid * 16 + fr;
;       const float df = __expf(lgf * (float)(ia + 1)), db = __expf(lgb * (float)(128 - ia));
; #pragma unroll
;       for (int ks = 0; ks < 4; ++ks) {
;         float tf[8], tb[8];
; #pragma unroll
;         for (int i = 0; i < 8; ++i) {
;           float qv = bfs(qa[ks][i]);
;           tf[i] = qv * df;
;           tb[i] = qv * db;
;         }
;         qf[ks] = pack8(tf); qb[ks] = pack8(tb);
;       }
;     }
; #pragma unroll
;     for (int ks = 0; ks < 4; ++ks) {
;       bf16x8 a = *reinterpret_cast<const bf16x8*>(Pw + fr * 136 + ks * 32 + fq * 8);
; #pragma unroll
;       for (int et = 0; et < 8; ++et) {
;         bf16x8 b = tr_frag(Vs + (ks * 32) * 136 + et * 16, 136, lane);
;         o1[et] = MFMA16(a, b, o1[et]);
;         bf16x8 bf = *reinterpret_cast<const bf16x8*>(Ks + (et * 16 + fr) * 136 + ks * 32 + fq * 8);
;         o1[et] = MFMA16(qf[ks], bf, o1[et]);
;         bf16x8 bb = *reinterpret_cast<const bf16x8*>(Sbl + (et * 16 + fr) * 136 + ks * 32 + fq * 8);
;         o1[et] = MFMA16(qb[ks], bb, o1[et]);
;       }
	v_mfma_f32_16x16x32_bf16 v[68:71], v[42:45], v[68:71], v[72:75]
	v_lshlrev_b32_e32 v114, 16, v53
	v_cvt_pk_bf16_f32 v28, v108, v109
	v_pk_mul_f32 v[108:109], v[0:1], v[20:21] op_sel_hi:[0,1]
	v_mfma_f32_16x16x32_bf16 v[58:61], v[22:25], v[58:61], 0
	v_mul_f32_e64 v20, v18, v20
	v_mul_f32_e64 v21, v18, v21
	v_cvt_pk_bf16_f32 v29, v112, v113
	v_pk_mul_f32 v[112:113], v[0:1], v[110:111] op_sel_hi:[0,1]
	s_waitcnt lgkmcnt(0)
	v_mfma_f32_16x16x32_bf16 v[86:89], v[46:49], v[86:89], v[68:71]
	s_nop 2
	ds_read_b128 v[70:73], v161
	ds_read_b64_tr_b16 v[64:65], v131 offset:36096
	ds_read_b64_tr_b16 v[68:69], v131 offset:36128
	ds_read_b128 v[74:77], v162
	v_pk_mul_f32 v[110:111], v[18:19], v[110:111] op_sel_hi:[0,1]
	s_waitcnt lgkmcnt(3)
	v_mfma_f32_16x16x32_bf16 v[58:61], v[42:45], v[70:73], v[58:61]
	ds_read_b128 v[70:73], v163
	v_pk_mul_f32 v[116:117], v[0:1], v[114:115] op_sel_hi:[0,1]
	s_waitcnt lgkmcnt(3)
	v_mfma_f32_16x16x32_bf16 v[62:65], v[22:25], v[62:65], 0
	s_waitcnt lgkmcnt(1)
	v_mfma_f32_16x16x32_bf16 v[58:61], v[46:49], v[74:77], v[58:61]
	v_mul_f32_e64 v74, v0, v50
	v_mul_f32_e64 v75, v0, v51
	v_pk_mul_f32 v[76:77], v[18:19], v[50:51] op_sel_hi:[0,1]
	ds_read_b128 v[50:53], v164
	s_waitcnt lgkmcnt(1)
	v_mfma_f32_16x16x32_bf16 v[62:65], v[42:45], v[70:73], v[62:65]
	v_mul_f32_e64 v70, v18, v114
	v_mul_f32_e64 v71, v18, v115
	v_cvt_pk_bf16_f32 v18, v20, v21
	v_cvt_pk_bf16_f32 v21, v70, v71
	ds_read_b128 v[70:73], v166
	s_waitcnt lgkmcnt(1)
	v_mfma_f32_16x16x32_bf16 v[62:65], v[46:49], v[50:53], v[62:65]
	ds_read_b128 v[50:53], v165
	v_cvt_pk_bf16_f32 v19, v110, v111
	v_cvt_pk_bf16_f32 v20, v76, v77
	v_mfma_f32_16x16x32_bf16 v[66:69], v[22:25], v[66:69], 0
	v_cvt_pk_bf16_f32 v22, v108, v109
	v_cvt_pk_bf16_f32 v23, v112, v113
	v_cvt_pk_bf16_f32 v24, v74, v75
	s_waitcnt lgkmcnt(0)
	v_mfma_f32_16x16x32_bf16 v[42:45], v[42:45], v[50:53], v[66:69]
	v_cvt_pk_bf16_f32 v25, v116, v117
	v_mfma_f32_16x16x32_bf16 v[70:73], v[46:49], v[70:73], v[42:45]
	ds_read_b128 v[74:77], v130 offset:64
	s_nop 4
	ds_read_b64_tr_b16 v[44:45], v131 offset:44608
	ds_read_b64_tr_b16 v[42:43], v131 offset:43520
	ds_read_b64_tr_b16 v[46:47], v131 offset:43552
	ds_read_b128 v[48:51], v142 offset:64
	s_waitcnt lgkmcnt(2)
	v_mfma_f32_16x16x32_bf16 v[42:45], v[74:77], v[42:45], v[78:81]
	s_waitcnt lgkmcnt(0)
	v_mfma_f32_16x16x32_bf16 v[42:45], v[38:41], v[48:51], v[42:45]
	ds_read_b128 v[48:51], v143 offset:64
	s_waitcnt lgkmcnt(0)
	v_mfma_f32_16x16x32_bf16 v[66:69], v[34:37], v[48:51], v[42:45]
	ds_read_b64_tr_b16 v[48:49], v131 offset:44640
	s_waitcnt lgkmcnt(0)
	v_mfma_f32_16x16x32_bf16 v[42:45], v[74:77], v[46:49], v[90:93]
	ds_read_b128 v[46:49], v142 offset:4416
	s_waitcnt lgkmcnt(0)
	v_mfma_f32_16x16x32_bf16 v[42:45], v[38:41], v[46:49], v[42:45]
	ds_read_b128 v[46:49], v144 offset:64
	s_waitcnt lgkmcnt(0)
	v_mfma_f32_16x16x32_bf16 v[42:45], v[34:37], v[46:49], v[42:45]
	ds_read_b64_tr_b16 v[46:47], v131 offset:43584
	ds_read_b64_tr_b16 v[48:49], v131 offset:44672
	ds_read_b128 v[50:53], v142 offset:8768
	s_waitcnt lgkmcnt(1)
	v_mfma_f32_16x16x32_bf16 v[46:49], v[74:77], v[46:49], v[54:57]
	s_waitcnt lgkmcnt(0)
	v_mfma_f32_16x16x32_bf16 v[46:49], v[38:41], v[50:53], v[46:49]
	ds_read_b128 v[50:53], v145 offset:64
	s_waitcnt lgkmcnt(0)
	v_mfma_f32_16x16x32_bf16 v[46:49], v[34:37], v[50:53], v[46:49]
	ds_read_b64_tr_b16 v[50:51], v131 offset:43616
	ds_read_b64_tr_b16 v[52:53], v131 offset:44704
	ds_read_b128 v[54:57], v146 offset:64
	s_waitcnt lgkmcnt(1)
	v_mfma_f32_16x16x32_bf16 v[50:53], v[74:77], v[50:53], v[82:85]
	s_waitcnt lgkmcnt(0)
	v_mfma_f32_16x16x32_bf16 v[50:53], v[38:41], v[54:57], v[50:53]
	ds_read_b128 v[54:57], v147 offset:64
	s_waitcnt lgkmcnt(0)
	v_mfma_f32_16x16x32_bf16 v[50:53], v[34:37], v[54:57], v[50:53]
	ds_read_b64_tr_b16 v[54:55], v131 offset:43648
	ds_read_b64_tr_b16 v[56:57], v131 offset:44736
	ds_read_b128 v[78:81], v159 offset:64
	s_waitcnt lgkmcnt(1)
	v_mfma_f32_16x16x32_bf16 v[54:57], v[74:77], v[54:57], v[86:89]
	s_waitcnt lgkmcnt(0)
	v_mfma_f32_16x16x32_bf16 v[54:57], v[38:41], v[78:81], v[54:57]
	ds_read_b128 v[78:81], v160 offset:64
	s_waitcnt lgkmcnt(0)
	v_mfma_f32_16x16x32_bf16 v[54:57], v[34:37], v[78:81], v[54:57]
	ds_read_b64_tr_b16 v[78:79], v131 offset:43680
	ds_read_b64_tr_b16 v[80:81], v131 offset:44768
	s_waitcnt lgkmcnt(0)
	v_mfma_f32_16x16x32_bf16 v[58:61], v[74:77], v[78:81], v[58:61]
	ds_read_b128 v[78:81], v161 offset:64
	s_waitcnt lgkmcnt(0)
	v_mfma_f32_16x16x32_bf16 v[58:61], v[38:41], v[78:81], v[58:61]
	ds_read_b128 v[78:81], v162 offset:64
	s_waitcnt lgkmcnt(0)
	v_mfma_f32_16x16x32_bf16 v[58:61], v[34:37], v[78:81], v[58:61]
	ds_read_b64_tr_b16 v[78:79], v131 offset:43712
	ds_read_b64_tr_b16 v[80:81], v131 offset:44800
	s_waitcnt lgkmcnt(0)
	v_mfma_f32_16x16x32_bf16 v[62:65], v[74:77], v[78:81], v[62:65]
	ds_read_b128 v[78:81], v163 offset:64
	s_waitcnt lgkmcnt(0)
	v_mfma_f32_16x16x32_bf16 v[62:65], v[38:41], v[78:81], v[62:65]
	ds_read_b128 v[78:81], v164 offset:64
	s_waitcnt lgkmcnt(0)
	v_mfma_f32_16x16x32_bf16 v[62:65], v[34:37], v[78:81], v[62:65]
	ds_read_b64_tr_b16 v[78:79], v131 offset:43744
	ds_read_b64_tr_b16 v[80:81], v131 offset:44832
	s_waitcnt lgkmcnt(0)
	v_mfma_f32_16x16x32_bf16 v[70:73], v[74:77], v[78:81], v[70:73]
	ds_read_b128 v[74:77], v165 offset:64
	s_waitcnt lgkmcnt(0)
	v_mfma_f32_16x16x32_bf16 v[38:41], v[38:41], v[74:77], v[70:73]
	s_nop 4
	ds_read_b128 v[70:73], v166 offset:64
	s_waitcnt lgkmcnt(0)
	v_mfma_f32_16x16x32_bf16 v[70:73], v[34:37], v[70:73], v[38:41]
	ds_read_b128 v[74:77], v130 offset:128
	ds_read_b64_tr_b16 v[36:37], v131 offset:53312
	ds_read_b64_tr_b16 v[34:35], v131 offset:52224
	ds_read_b64_tr_b16 v[38:39], v131 offset:52256
	s_waitcnt lgkmcnt(1)
; #define MFMA16(a, b, c) __builtin_amdgcn_mfma_f32_16x16x32_bf16(a, b, c, 0, 0, 0)
; __device__ __forceinline__ void phase_ret_o(PP p, const int g_wid, int layer) {
;     ...
; #pragma unroll
;     for (int ks = 0; ks < 4; ++ks) {
;       bf16x8 a = *reinterpret_cast<const bf16x8*>(Pw + fr * 136 + ks * 32 + fq * 8);
; #pragma unroll
;       for (int et = 0; et < 8; ++et) {
;         bf16x8 b = tr_frag(Vs + (ks * 32) * 136 + et * 16, 136, lane);
;         o1[et] = MFMA16(a, b, o1[et]);
;         bf16x8 bf = *reinterpret_cast<const bf16x8*>(Ks + (et * 16 + fr) * 136 + ks * 32 + fq * 8);
;         o1[et] = MFMA16(qf[ks], bf, o1[et]);
;         bf16x8 bb = *reinterpret_cast<const bf16x8*>(Sbl + (et * 16 + fr) * 136 + ks * 32 + fq * 8);
;         o1[et] = MFMA16(qb[ks], bb, o1[et]);
;       }
	v_mfma_f32_16x16x32_bf16 v[34:37], v[74:77], v[34:37], v[66:69]
	s_nop 2
	ds_read_b128 v[66:69], v142 offset:128
	ds_read_b64_tr_b16 v[40:41], v131 offset:53344
	s_waitcnt lgkmcnt(1)
	v_mfma_f32_16x16x32_bf16 v[34:37], v[30:33], v[66:69], v[34:37]
	ds_read_b128 v[66:69], v143 offset:128
	s_waitcnt lgkmcnt(0)
	v_mfma_f32_16x16x32_bf16 v[66:69], v[26:29], v[66:69], v[34:37]
	v_mfma_f32_16x16x32_bf16 v[34:37], v[74:77], v[38:41], v[42:45]
	ds_read_b128 v[38:41], v142 offset:4480
	s_waitcnt lgkmcnt(0)
	v_mfma_f32_16x16x32_bf16 v[34:37], v[30:33], v[38:41], v[34:37]
	ds_read_b128 v[38:41], v144 offset:128
	s_waitcnt lgkmcnt(0)
	v_mfma_f32_16x16x32_bf16 v[34:37], v[26:29], v[38:41], v[34:37]
	ds_read_b64_tr_b16 v[38:39], v131 offset:52288
	ds_read_b64_tr_b16 v[40:41], v131 offset:53376
	ds_read_b128 v[42:45], v142 offset:8832
	s_waitcnt lgkmcnt(1)
	v_mfma_f32_16x16x32_bf16 v[38:41], v[74:77], v[38:41], v[46:49]
	s_waitcnt lgkmcnt(0)
	v_mfma_f32_16x16x32_bf16 v[38:41], v[30:33], v[42:45], v[38:41]
	ds_read_b128 v[42:45], v145 offset:128
	s_waitcnt lgkmcnt(0)
	v_mfma_f32_16x16x32_bf16 v[38:41], v[26:29], v[42:45], v[38:41]
	ds_read_b64_tr_b16 v[42:43], v131 offset:52320
	ds_read_b64_tr_b16 v[44:45], v131 offset:53408
	ds_read_b128 v[46:49], v146 offset:128
	s_waitcnt lgkmcnt(1)
	v_mfma_f32_16x16x32_bf16 v[42:45], v[74:77], v[42:45], v[50:53]
	s_waitcnt lgkmcnt(0)
	v_mfma_f32_16x16x32_bf16 v[42:45], v[30:33], v[46:49], v[42:45]
	ds_read_b128 v[46:49], v147 offset:128
	s_waitcnt lgkmcnt(0)
	v_mfma_f32_16x16x32_bf16 v[42:45], v[26:29], v[46:49], v[42:45]
	ds_read_b64_tr_b16 v[46:47], v131 offset:52352
	ds_read_b64_tr_b16 v[48:49], v131 offset:53440
	ds_read_b128 v[50:53], v159 offset:128
	s_waitcnt lgkmcnt(1)
	v_mfma_f32_16x16x32_bf16 v[46:49], v[74:77], v[46:49], v[54:57]
	s_waitcnt lgkmcnt(0)
	v_mfma_f32_16x16x32_bf16 v[46:49], v[30:33], v[50:53], v[46:49]
	ds_read_b128 v[50:53], v160 offset:128
	s_waitcnt lgkmcnt(0)
	v_mfma_f32_16x16x32_bf16 v[46:49], v[26:29], v[50:53], v[46:49]
	ds_read_b64_tr_b16 v[50:51], v131 offset:52384
	ds_read_b64_tr_b16 v[52:53], v131 offset:53472
	ds_read_b128 v[54:57], v161 offset:128
	s_waitcnt lgkmcnt(1)
	v_mfma_f32_16x16x32_bf16 v[50:53], v[74:77], v[50:53], v[58:61]
	s_waitcnt lgkmcnt(0)
	v_mfma_f32_16x16x32_bf16 v[50:53], v[30:33], v[54:57], v[50:53]
	ds_read_b128 v[54:57], v162 offset:128
	s_waitcnt lgkmcnt(0)
	v_mfma_f32_16x16x32_bf16 v[54:57], v[26:29], v[54:57], v[50:53]
	s_nop 4
	ds_read_b64_tr_b16 v[50:51], v131 offset:52416
	ds_read_b64_tr_b16 v[52:53], v131 offset:53504
	ds_read_b128 v[58:61], v163 offset:128
	s_waitcnt lgkmcnt(1)
	v_mfma_f32_16x16x32_bf16 v[50:53], v[74:77], v[50:53], v[62:65]
	s_waitcnt lgkmcnt(0)
	v_mfma_f32_16x16x32_bf16 v[50:53], v[30:33], v[58:61], v[50:53]
	ds_read_b128 v[58:61], v164 offset:128
	s_waitcnt lgkmcnt(0)
	v_mfma_f32_16x16x32_bf16 v[58:61], v[26:29], v[58:61], v[50:53]
	s_nop 4
	ds_read_b64_tr_b16 v[50:51], v131 offset:52448
	ds_read_b64_tr_b16 v[52:53], v131 offset:53536
	ds_read_b128 v[62:65], v165 offset:128
	s_waitcnt lgkmcnt(1)
	v_mfma_f32_16x16x32_bf16 v[50:53], v[74:77], v[50:53], v[70:73]
	s_waitcnt lgkmcnt(0)
	v_mfma_f32_16x16x32_bf16 v[30:33], v[30:33], v[62:65], v[50:53]
	s_nop 5
	ds_read_b128 v[50:53], v166 offset:128
	s_waitcnt lgkmcnt(0)
	v_mfma_f32_16x16x32_bf16 v[62:65], v[26:29], v[50:53], v[30:33]
	ds_read_b128 v[70:73], v130 offset:192
	ds_read_b64_tr_b16 v[28:29], v131 offset:62016
	ds_read_b64_tr_b16 v[26:27], v131 offset:60928
	ds_read_b64_tr_b16 v[30:31], v131 offset:60960
	ds_read_b128 v[50:53], v142 offset:192
	ds_read_b64_tr_b16 v[32:33], v131 offset:62048
	s_waitcnt lgkmcnt(3)
	v_mfma_f32_16x16x32_bf16 v[26:29], v[70:73], v[26:29], v[66:69]
	s_waitcnt lgkmcnt(1)
	v_mfma_f32_16x16x32_bf16 v[26:29], v[18:21], v[50:53], v[26:29]
	ds_read_b128 v[50:53], v143 offset:192
	s_waitcnt lgkmcnt(1)
; #define SCHED __builtin_amdgcn_sched_barrier(0)
; #define MFMA16(a, b, c) __builtin_amdgcn_mfma_f32_16x16x32_bf16(a, b, c, 0, 0, 0)
; __device__ __forceinline__ void phase_ret_o(PP p, const int g_wid, int layer) {
;     ...
; #pragma unroll
;     for (int ks = 0; ks < 4; ++ks) {
;       bf16x8 a = *reinterpret_cast<const bf16x8*>(Pw + fr * 136 + ks * 32 + fq * 8);
; #pragma unroll
;       for (int et = 0; et < 8; ++et) {
;         bf16x8 b = tr_frag(Vs + (ks * 32) * 136 + et * 16, 136, lane);
;         o1[et] = MFMA16(a, b, o1[et]);
;         bf16x8 bf = *reinterpret_cast<const bf16x8*>(Ks + (et * 16 + fr) * 136 + ks * 32 + fq * 8);
;         o1[et] = MFMA16(qf[ks], bf, o1[et]);
;         bf16x8 bb = *reinterpret_cast<const bf16x8*>(Sbl + (et * 16 + fr) * 136 + ks * 32 + fq * 8);
;         o1[et] = MFMA16(qb[ks], bb, o1[et]);
;       }
;       SCHED;
;     }
;     SCHED;
;     const int erow = lane >> 2, ec0 = (lane & 3) * 32;
;     const int epos = t0 + wid * 16 + erow;
;     bf16x8 gv[4];
;     if (epos < L) {
;       const u16* gp = Pr + (long)(base + epos) * 2048 + 1536 + hd * 128 + ec0;
; #pragma unroll
;       for (int k = 0; k < 4; ++k) gv[k] = *reinterpret_cast<const bf16x8*>(gp + 8 * k);
	v_mfma_f32_16x16x32_bf16 v[30:33], v[70:73], v[30:33], v[34:37]
	s_nop 2
	ds_read_b128 v[34:37], v142 offset:4544
	s_waitcnt lgkmcnt(0)
	v_mfma_f32_16x16x32_bf16 v[30:33], v[18:21], v[34:37], v[30:33]
	ds_read_b128 v[34:37], v144 offset:192
	s_waitcnt lgkmcnt(0)
	v_mfma_f32_16x16x32_bf16 v[30:33], v[22:25], v[34:37], v[30:33]
	ds_read_b64_tr_b16 v[34:35], v131 offset:60992
	ds_read_b64_tr_b16 v[36:37], v131 offset:62080
	s_waitcnt lgkmcnt(0)
	v_mfma_f32_16x16x32_bf16 v[34:37], v[70:73], v[34:37], v[38:41]
	s_nop 2
	ds_read_b128 v[38:41], v142 offset:8896
	s_waitcnt lgkmcnt(0)
	v_mfma_f32_16x16x32_bf16 v[34:37], v[18:21], v[38:41], v[34:37]
	ds_read_b128 v[38:41], v145 offset:192
	s_waitcnt lgkmcnt(0)
	v_mfma_f32_16x16x32_bf16 v[34:37], v[22:25], v[38:41], v[34:37]
	ds_read_b64_tr_b16 v[38:39], v131 offset:61024
	ds_read_b64_tr_b16 v[40:41], v131 offset:62112
	s_waitcnt lgkmcnt(0)
	v_mfma_f32_16x16x32_bf16 v[38:41], v[70:73], v[38:41], v[42:45]
	s_nop 2
	ds_read_b128 v[42:45], v146 offset:192
	s_waitcnt lgkmcnt(0)
	v_mfma_f32_16x16x32_bf16 v[38:41], v[18:21], v[42:45], v[38:41]
	ds_read_b128 v[42:45], v147 offset:192
	v_mfma_f32_16x16x32_bf16 v[26:29], v[22:25], v[50:53], v[26:29]
	s_waitcnt lgkmcnt(0)
	v_mfma_f32_16x16x32_bf16 v[50:53], v[22:25], v[42:45], v[38:41]
	s_nop 3
	ds_read_b64_tr_b16 v[38:39], v131 offset:61056
	ds_read_b64_tr_b16 v[40:41], v131 offset:62144
	ds_read_b128 v[42:45], v159 offset:192
	s_waitcnt lgkmcnt(1)
	v_mfma_f32_16x16x32_bf16 v[38:41], v[70:73], v[38:41], v[46:49]
	s_waitcnt lgkmcnt(0)
	v_mfma_f32_16x16x32_bf16 v[38:41], v[18:21], v[42:45], v[38:41]
	ds_read_b128 v[42:45], v160 offset:192
	s_waitcnt lgkmcnt(0)
	v_mfma_f32_16x16x32_bf16 v[38:41], v[22:25], v[42:45], v[38:41]
	ds_read_b64_tr_b16 v[42:43], v131 offset:61088
	ds_read_b64_tr_b16 v[44:45], v131 offset:62176
	ds_read_b128 v[46:49], v161 offset:192
	s_waitcnt lgkmcnt(1)
	v_mfma_f32_16x16x32_bf16 v[42:45], v[70:73], v[42:45], v[54:57]
	s_waitcnt lgkmcnt(0)
	v_mfma_f32_16x16x32_bf16 v[42:45], v[18:21], v[46:49], v[42:45]
	ds_read_b128 v[46:49], v162 offset:192
	s_waitcnt lgkmcnt(0)
	v_mfma_f32_16x16x32_bf16 v[42:45], v[22:25], v[46:49], v[42:45]
	ds_read_b64_tr_b16 v[46:47], v131 offset:61120
	ds_read_b64_tr_b16 v[48:49], v131 offset:62208
	ds_read_b128 v[54:57], v163 offset:192
	s_waitcnt lgkmcnt(1)
	v_mfma_f32_16x16x32_bf16 v[46:49], v[70:73], v[46:49], v[58:61]
	s_waitcnt lgkmcnt(0)
	v_mfma_f32_16x16x32_bf16 v[46:49], v[18:21], v[54:57], v[46:49]
	ds_read_b128 v[54:57], v164 offset:192
	s_waitcnt lgkmcnt(0)
	v_mfma_f32_16x16x32_bf16 v[46:49], v[22:25], v[54:57], v[46:49]
	ds_read_b64_tr_b16 v[54:55], v131 offset:61152
	ds_read_b64_tr_b16 v[56:57], v131 offset:62240
	ds_read_b128 v[58:61], v165 offset:192
	s_waitcnt lgkmcnt(1)
	v_mfma_f32_16x16x32_bf16 v[54:57], v[70:73], v[54:57], v[62:65]
	s_waitcnt lgkmcnt(0)
	v_mfma_f32_16x16x32_bf16 v[18:21], v[18:21], v[58:61], v[54:57]
	s_nop 5
	ds_read_b128 v[54:57], v166 offset:192
	s_waitcnt lgkmcnt(0)
	v_mfma_f32_16x16x32_bf16 v[18:21], v[22:25], v[54:57], v[18:21]
	v_or_b32_e32 v0, v168, v132
	v_cmp_gt_i32_e32 vcc, s35, v0
	v_cmp_le_i32_e64 s[6:7], s35, v0
	s_and_saveexec_b64 s[20:21], s[6:7]
	s_xor_b64 s[6:7], exec, s[20:21]
	s_lshl_b32 s8, s31, 7
	s_or_saveexec_b64 s[6:7], s[6:7]
	v_mov_b32_e32 v24, s8
	v_add_u32_e32 v22, s34, v0
	v_lshlrev_b32_e32 v0, 1, v98
	s_xor_b64 exec, exec, s[6:7]
	s_cbranch_execz .LBB0_203
	v_ashrrev_i32_e32 v23, 31, v22
	v_lshlrev_b64 v[2:3], 12, v[22:23]
	v_lshl_add_u64 v[2:3], s[14:15], 0, v[2:3]
	s_lshl_b32 s54, s31, 8
	v_lshl_add_u64 v[2:3], v[2:3], 0, s[54:55]
	v_lshl_add_u64 v[2:3], v[2:3], 0, v[0:1]
	global_load_dwordx4 v[14:17], v[2:3], off offset:3072
	global_load_dwordx4 v[10:13], v[2:3], off offset:3088
	global_load_dwordx4 v[6:9], v[2:3], off offset:3104
	s_nop 0
	global_load_dwordx4 v[2:5], v[2:3], off offset:3120
	s_lshl_b32 s8, s31, 7
	v_mov_b32_e32 v24, s8
